# DF attention loop: coalesced 10 paired lgkmcnt waits before independent MFMA pairs (on top of v47)
# baseline (speedup 1.0000x reference)
.LBB0_258:
	global_load_dwordx4 v[158:161], v[186:187], off
	global_load_dwordx4 v[154:157], v[188:189], off
	global_load_dwordx4 v[150:153], v[182:183], off offset:256
	global_load_dwordx4 v[146:149], v[184:185], off offset:256
	ds_read_b128 v[96:99], v219 offset:18432
	ds_read_b128 v[222:225], v219 offset:18464
	ds_read_b128 v[100:103], v219 offset:23040
	ds_read_b128 v[226:229], v219 offset:23072
	ds_read_b128 v[230:233], v219 offset:18496
	ds_read_b128 v[234:237], v219 offset:18528
	ds_read_b128 v[238:241], v219 offset:23104
	ds_read_b128 v[242:245], v219 offset:23136
	v_mul_f32_e32 v190, 0x3e38aa3b, v220
	s_waitcnt lgkmcnt(7)
	v_mfma_f32_32x32x16_bf16 v[112:127], v[96:99], v[142:145], 0
	v_fma_f32 v80, v80, s78, -v190
	v_fma_f32 v81, v81, s78, -v190
	v_fma_f32 v82, v82, s78, -v190
	v_fma_f32 v83, v83, s78, -v190
	v_exp_f32_e32 v80, v80
	v_exp_f32_e32 v81, v81
	v_exp_f32_e32 v82, v82
	v_exp_f32_e32 v83, v83
	v_pk_add_f32 v[96:97], v[80:81], 0 op_sel_hi:[1,0]
	v_cvt_pk_bf16_f32 v80, v80, v81
	v_pk_add_f32 v[246:247], v[82:83], v[96:97]
	v_cvt_pk_bf16_f32 v81, v82, v83
	s_waitcnt lgkmcnt(5)
	v_mfma_f32_32x32x16_bf16 v[96:111], v[100:103], v[142:145], 0
	v_mfma_f32_32x32x16_bf16 v[112:127], v[222:225], v[136:139], v[112:127]
	v_fma_f32 v82, v84, s78, -v190
	v_fma_f32 v83, v85, s78, -v190
	v_fma_f32 v84, v86, s78, -v190
	v_fma_f32 v85, v87, s78, -v190
	v_exp_f32_e32 v82, v82
	v_exp_f32_e32 v83, v83
	v_exp_f32_e32 v84, v84
	v_exp_f32_e32 v85, v85
	v_pk_add_f32 v[86:87], v[82:83], v[246:247]
	v_cvt_pk_bf16_f32 v82, v82, v83
	v_pk_add_f32 v[86:87], v[84:85], v[86:87]
	v_cvt_pk_bf16_f32 v83, v84, v85
	s_waitcnt lgkmcnt(3)
	v_mfma_f32_32x32x16_bf16 v[96:111], v[226:229], v[136:139], v[96:111]
	v_mfma_f32_32x32x16_bf16 v[112:127], v[230:233], v[132:135], v[112:127]
	v_fma_f32 v84, v88, s78, -v190
	v_fma_f32 v85, v89, s78, -v190
	v_fma_f32 v88, v90, s78, -v190
	v_fma_f32 v89, v91, s78, -v190
	v_exp_f32_e32 v84, v84
	v_exp_f32_e32 v85, v85
	v_exp_f32_e32 v88, v88
	v_exp_f32_e32 v89, v89
	v_pk_add_f32 v[86:87], v[84:85], v[86:87]
	v_cvt_pk_bf16_f32 v84, v84, v85
	v_pk_add_f32 v[86:87], v[88:89], v[86:87]
	v_cvt_pk_bf16_f32 v85, v88, v89
	s_waitcnt lgkmcnt(1)
	v_mfma_f32_32x32x16_bf16 v[96:111], v[238:241], v[132:135], v[96:111]
	v_mfma_f32_32x32x16_bf16 v[112:127], v[234:237], v[128:131], v[112:127]
	v_fma_f32 v88, v92, s78, -v190
	v_fma_f32 v89, v93, s78, -v190
	v_fma_f32 v90, v94, s78, -v190
	v_fma_f32 v91, v95, s78, -v190
	v_exp_f32_e32 v88, v88
	v_exp_f32_e32 v89, v89
	v_exp_f32_e32 v90, v90
	v_exp_f32_e32 v91, v91
	v_pk_add_f32 v[86:87], v[88:89], v[86:87]
	s_nop 0
	v_pk_add_f32 v[246:247], v[90:91], v[86:87]
	v_cvt_pk_bf16_f32 v86, v88, v89
	v_cvt_pk_bf16_f32 v87, v90, v91
	s_waitcnt lgkmcnt(0)
	v_mfma_f32_32x32x16_bf16 v[96:111], v[242:245], v[128:131], v[96:111]
	s_mul_i32 s27, s30, 0x4800
	s_add_i32 s24, s30, 1
	v_add_u32_e32 v221, s27, v218
	s_cmp_lg_u32 s30, 2
	ds_read_b128 v[88:91], v221 offset:36864
	ds_read_b128 v[92:95], v221 offset:41472
	ds_read_b128 v[222:225], v221 offset:46080
	ds_read_b128 v[226:229], v221 offset:50688
	s_cselect_b32 s24, s24, 0
	s_add_i32 s25, s24, 1
	s_cmp_lg_u32 s24, 2
	s_cselect_b32 s30, s25, 0
	s_mul_i32 s25, s30, 0x4800
	s_add_i32 s27, s25, 0
	v_add_u32_e32 v248, s27, v180
	v_add_u32_e32 v249, s27, v178
	ds_read_b128 v[230:233], v221 offset:36896
	ds_read_b128 v[234:237], v221 offset:41504
	ds_read_b128 v[238:241], v221 offset:46112
	ds_read_b128 v[242:245], v221 offset:50720
	s_waitcnt lgkmcnt(7)
	v_mfma_f32_32x32x16_bf16 v[16:31], v[88:91], v[80:83], v[16:31]
	v_fma_f32 v64, v64, s78, -v190
	v_fma_f32 v65, v65, s78, -v190
	v_fma_f32 v66, v66, s78, -v190
	v_fma_f32 v67, v67, s78, -v190
	v_exp_f32_e32 v64, v64
	v_exp_f32_e32 v65, v65
	v_exp_f32_e32 v66, v66
	v_exp_f32_e32 v67, v67
	v_pk_add_f32 v[88:89], v[64:65], v[246:247]
	v_cvt_pk_bf16_f32 v64, v64, v65
	v_pk_add_f32 v[88:89], v[66:67], v[88:89]
	v_cvt_pk_bf16_f32 v65, v66, v67
	s_waitcnt lgkmcnt(5)
	v_mfma_f32_32x32x16_bf16 v[48:63], v[92:95], v[80:83], v[48:63]
	v_mfma_f32_32x32x16_bf16 v[32:47], v[222:225], v[80:83], v[32:47]
	v_fma_f32 v66, v68, s78, -v190
	v_fma_f32 v67, v69, s78, -v190
	v_fma_f32 v68, v70, s78, -v190
	v_fma_f32 v69, v71, s78, -v190
	v_exp_f32_e32 v66, v66
	v_exp_f32_e32 v67, v67
	v_exp_f32_e32 v68, v68
	v_exp_f32_e32 v69, v69
	v_pk_add_f32 v[70:71], v[66:67], v[88:89]
	v_cvt_pk_bf16_f32 v66, v66, v67
	v_pk_add_f32 v[222:223], v[68:69], v[70:71]
	v_cvt_pk_bf16_f32 v67, v68, v69
	s_waitcnt lgkmcnt(4)
	v_mfma_f32_32x32x16_bf16 v[0:15], v[226:229], v[80:83], v[0:15]
	s_waitcnt vmcnt(3)
	ds_write_b128 v217, v[158:161]
	ds_read_b128 v[68:71], v221 offset:36928
	ds_read_b128 v[80:83], v221 offset:41536
	ds_read_b128 v[88:91], v221 offset:46144
	ds_read_b128 v[92:95], v221 offset:50752
	s_waitcnt lgkmcnt(8)
	v_mfma_f32_32x32x16_bf16 v[16:31], v[230:233], v[84:87], v[16:31]
	v_fma_f32 v72, v72, s78, -v190
	v_fma_f32 v73, v73, s78, -v190
	v_fma_f32 v74, v74, s78, -v190
	v_fma_f32 v75, v75, s78, -v190
	v_exp_f32_e32 v72, v72
	v_exp_f32_e32 v73, v73
	v_exp_f32_e32 v74, v74
	v_exp_f32_e32 v75, v75
	v_pk_add_f32 v[158:159], v[72:73], v[222:223]
	v_cvt_pk_bf16_f32 v72, v72, v73
	v_pk_add_f32 v[158:159], v[74:75], v[158:159]
	v_cvt_pk_bf16_f32 v73, v74, v75
	s_waitcnt lgkmcnt(6)
	v_mfma_f32_32x32x16_bf16 v[48:63], v[234:237], v[84:87], v[48:63]
	v_mfma_f32_32x32x16_bf16 v[32:47], v[238:241], v[84:87], v[32:47]
	v_fma_f32 v74, v76, s78, -v190
	v_fma_f32 v75, v77, s78, -v190
	v_fma_f32 v76, v78, s78, -v190
	v_fma_f32 v77, v79, s78, -v190
	v_exp_f32_e32 v74, v74
	v_exp_f32_e32 v75, v75
	v_exp_f32_e32 v76, v76
	v_exp_f32_e32 v77, v77
	v_pk_add_f32 v[78:79], v[74:75], v[158:159]
	v_cvt_pk_bf16_f32 v74, v74, v75
	v_pk_add_f32 v[222:223], v[76:77], v[78:79]
	v_cvt_pk_bf16_f32 v75, v76, v77
	s_waitcnt lgkmcnt(5)
	v_mfma_f32_32x32x16_bf16 v[0:15], v[242:245], v[84:87], v[0:15]
	s_waitcnt vmcnt(2)
	ds_write_b128 v216, v[154:157]
	ds_read_b128 v[76:79], v221 offset:36960
	ds_read_b128 v[84:87], v221 offset:41568
	ds_read_b128 v[154:157], v221 offset:46176
	ds_read_b128 v[158:161], v221 offset:50784
	s_waitcnt lgkmcnt(8)
	v_mfma_f32_32x32x16_bf16 v[16:31], v[68:71], v[64:67], v[16:31]
	s_mov_b32 s27, 0xf149f2ca
	v_max3_f32 v68, v112, s27, v113
	v_max3_f32 v68, v68, v114, v115
	v_max3_f32 v68, v68, v116, v117
	v_max3_f32 v68, v68, v118, v119
	s_waitcnt lgkmcnt(6)
	v_mfma_f32_32x32x16_bf16 v[48:63], v[80:83], v[64:67], v[48:63]
	v_mfma_f32_32x32x16_bf16 v[32:47], v[88:91], v[64:67], v[32:47]
	v_max3_f32 v68, v68, v120, v121
	v_max3_f32 v68, v68, v122, v123
	v_max3_f32 v68, v68, v124, v125
	v_max3_f32 v68, v68, v126, v127
	s_waitcnt lgkmcnt(5)
	v_mfma_f32_32x32x16_bf16 v[0:15], v[92:95], v[64:67], v[0:15]
	s_waitcnt vmcnt(1)
	ds_write_b128 v249, v[150:153] offset:36864
	s_waitcnt lgkmcnt(4)
	v_mfma_f32_32x32x16_bf16 v[16:31], v[76:79], v[72:75], v[16:31]
	v_max3_f32 v64, v68, v96, v97
	v_max3_f32 v64, v64, v98, v99
	v_max3_f32 v64, v64, v100, v101
	v_max3_f32 v64, v64, v102, v103
	s_waitcnt lgkmcnt(2)
	v_mfma_f32_32x32x16_bf16 v[48:63], v[84:87], v[72:75], v[48:63]
	v_mfma_f32_32x32x16_bf16 v[32:47], v[154:157], v[72:75], v[32:47]
	v_max3_f32 v64, v64, v104, v105
	v_max3_f32 v64, v64, v106, v107
	v_max3_f32 v64, v64, v108, v109
	v_max3_f32 v64, v64, v110, v111
	s_waitcnt lgkmcnt(1)
	v_mfma_f32_32x32x16_bf16 v[0:15], v[158:161], v[72:75], v[0:15]
	s_waitcnt vmcnt(0)
	ds_write_b128 v248, v[146:149] offset:36864
	v_add_f32_e32 v65, v222, v223
	v_add_f32_e32 v158, v191, v65
	v_mov_b32_e32 v65, v64
	s_nop 1
	v_permlane32_swap_b32_e32 v64, v65
	v_max_f32_e32 v64, v64, v65
	v_sub_f32_e32 v65, v64, v220
	v_mul_f32_e32 v65, 0x3e38aa3b, v65
	v_cmp_lt_f32_e32 vcc, s5, v65
	s_cbranch_vccz .LBB0_260
	v_max_f32_e32 v64, v64, v64
	v_max_f32_e32 v65, v220, v220
	v_max_f32_e32 v65, v65, v64
	v_sub_f32_e32 v64, v220, v65
	v_mul_f32_e32 v64, 0x3e38aa3b, v64
	v_exp_f32_e32 v64, v64
	v_mul_f32_e32 v190, 0x3e38aa3b, v65
	v_mov_b32_e32 v220, v65
	v_pk_mul_f32 v[30:31], v[30:31], v[64:65] op_sel_hi:[1,0]
	v_pk_mul_f32 v[28:29], v[28:29], v[64:65] op_sel_hi:[1,0]
	v_pk_mul_f32 v[26:27], v[26:27], v[64:65] op_sel_hi:[1,0]
	v_pk_mul_f32 v[24:25], v[24:25], v[64:65] op_sel_hi:[1,0]
	v_pk_mul_f32 v[22:23], v[22:23], v[64:65] op_sel_hi:[1,0]
	v_pk_mul_f32 v[20:21], v[20:21], v[64:65] op_sel_hi:[1,0]
	v_pk_mul_f32 v[18:19], v[18:19], v[64:65] op_sel_hi:[1,0]
	v_pk_mul_f32 v[16:17], v[16:17], v[64:65] op_sel_hi:[1,0]
	v_pk_mul_f32 v[62:63], v[62:63], v[64:65] op_sel_hi:[1,0]
	v_pk_mul_f32 v[60:61], v[60:61], v[64:65] op_sel_hi:[1,0]
	v_pk_mul_f32 v[58:59], v[58:59], v[64:65] op_sel_hi:[1,0]
	v_pk_mul_f32 v[56:57], v[56:57], v[64:65] op_sel_hi:[1,0]
	v_pk_mul_f32 v[54:55], v[54:55], v[64:65] op_sel_hi:[1,0]
	v_pk_mul_f32 v[52:53], v[52:53], v[64:65] op_sel_hi:[1,0]
	v_pk_mul_f32 v[50:51], v[50:51], v[64:65] op_sel_hi:[1,0]
	v_pk_mul_f32 v[48:49], v[48:49], v[64:65] op_sel_hi:[1,0]
	v_pk_mul_f32 v[46:47], v[46:47], v[64:65] op_sel_hi:[1,0]
	v_pk_mul_f32 v[44:45], v[44:45], v[64:65] op_sel_hi:[1,0]
	v_pk_mul_f32 v[42:43], v[42:43], v[64:65] op_sel_hi:[1,0]
	v_pk_mul_f32 v[40:41], v[40:41], v[64:65] op_sel_hi:[1,0]
	v_pk_mul_f32 v[38:39], v[38:39], v[64:65] op_sel_hi:[1,0]
	v_pk_mul_f32 v[36:37], v[36:37], v[64:65] op_sel_hi:[1,0]
	v_pk_mul_f32 v[34:35], v[34:35], v[64:65] op_sel_hi:[1,0]
	v_pk_mul_f32 v[32:33], v[32:33], v[64:65] op_sel_hi:[1,0]
	v_pk_mul_f32 v[14:15], v[14:15], v[64:65] op_sel_hi:[1,0]
	v_pk_mul_f32 v[12:13], v[12:13], v[64:65] op_sel_hi:[1,0]
	v_pk_mul_f32 v[10:11], v[10:11], v[64:65] op_sel_hi:[1,0]
	v_pk_mul_f32 v[8:9], v[8:9], v[64:65] op_sel_hi:[1,0]
	v_pk_mul_f32 v[6:7], v[6:7], v[64:65] op_sel_hi:[1,0]
	v_pk_mul_f32 v[4:5], v[4:5], v[64:65] op_sel_hi:[1,0]
	v_pk_mul_f32 v[2:3], v[2:3], v[64:65] op_sel_hi:[1,0]
	v_pk_mul_f32 v[0:1], v[0:1], v[64:65] op_sel_hi:[1,0]
	v_mul_f32_e32 v158, v158, v64
.LBB0_260:
	s_mov_b64 s[98:99], 0x2000
	s_waitcnt lgkmcnt(0)
	v_lshl_add_u64 v[64:65], v[186:187], 0, s[98:99]
	s_barrier
	global_load_dwordx4 v[222:225], v[64:65], off
	v_lshl_add_u64 v[64:65], v[188:189], 0, s[98:99]
	v_mov_b32_e32 v191, v190
	global_load_dwordx4 v[154:157], v[64:65], off
	global_load_dwordx4 v[150:153], v[182:183], off offset:384
	global_load_dwordx4 v[146:149], v[184:185], off offset:384
	ds_read_b128 v[64:67], v219
	ds_read_b128 v[192:195], v219 offset:32
	ds_read_b128 v[68:71], v219 offset:4608
	ds_read_b128 v[196:199], v219 offset:4640
	ds_read_b128 v[226:229], v219 offset:64
	ds_read_b128 v[230:233], v219 offset:96
	ds_read_b128 v[234:237], v219 offset:4672
	ds_read_b128 v[238:241], v219 offset:4704
	s_waitcnt lgkmcnt(7)
	v_mfma_f32_32x32x16_bf16 v[80:95], v[64:67], v[142:145], 0
	v_fma_f32 v72, v112, s78, -v190
	v_fma_f32 v73, v113, s78, -v191
	v_fma_f32 v74, v114, s78, -v190
	v_fma_f32 v75, v115, s78, -v191
	v_exp_f32_e32 v72, v72
	v_exp_f32_e32 v73, v73
	v_exp_f32_e32 v74, v74
	v_exp_f32_e32 v75, v75
	v_pk_add_f32 v[64:65], v[72:73], 0 op_sel_hi:[1,0]
	v_cvt_pk_bf16_f32 v112, v72, v73
	v_pk_add_f32 v[114:115], v[74:75], v[64:65]
	v_cvt_pk_bf16_f32 v113, v74, v75
	s_waitcnt lgkmcnt(5)
	v_mfma_f32_32x32x16_bf16 v[64:79], v[68:71], v[142:145], 0
	v_mfma_f32_32x32x16_bf16 v[80:95], v[192:195], v[136:139], v[80:95]
	v_fma_f32 v116, v116, s78, -v190
	v_fma_f32 v117, v117, s78, -v191
	v_fma_f32 v118, v118, s78, -v190
	v_fma_f32 v119, v119, s78, -v191
	v_exp_f32_e32 v116, v116
	v_exp_f32_e32 v117, v117
	v_exp_f32_e32 v118, v118
	v_exp_f32_e32 v119, v119
	v_pk_add_f32 v[114:115], v[116:117], v[114:115]
	s_nop 0
	v_pk_add_f32 v[160:161], v[118:119], v[114:115]
	v_cvt_pk_bf16_f32 v114, v116, v117
	v_cvt_pk_bf16_f32 v115, v118, v119
	s_waitcnt lgkmcnt(3)
	v_mfma_f32_32x32x16_bf16 v[64:79], v[196:199], v[136:139], v[64:79]
	v_mfma_f32_32x32x16_bf16 v[80:95], v[226:229], v[132:135], v[80:95]
	v_fma_f32 v116, v120, s78, -v190
	v_fma_f32 v117, v121, s78, -v191
	v_fma_f32 v118, v122, s78, -v190
	v_fma_f32 v119, v123, s78, -v191
	v_exp_f32_e32 v116, v116
	v_exp_f32_e32 v117, v117
	v_exp_f32_e32 v118, v118
	v_exp_f32_e32 v119, v119
	v_pk_add_f32 v[120:121], v[116:117], v[160:161]
	v_cvt_pk_bf16_f32 v116, v116, v117
	v_pk_add_f32 v[120:121], v[118:119], v[120:121]
	v_cvt_pk_bf16_f32 v117, v118, v119
	s_waitcnt lgkmcnt(1)
	v_mfma_f32_32x32x16_bf16 v[64:79], v[234:237], v[132:135], v[64:79]
	v_mfma_f32_32x32x16_bf16 v[80:95], v[230:233], v[128:131], v[80:95]
	v_fma_f32 v118, v124, s78, -v190
	v_fma_f32 v119, v125, s78, -v191
	v_fma_f32 v122, v126, s78, -v190
	v_fma_f32 v123, v127, s78, -v191
	v_exp_f32_e32 v118, v118
	v_exp_f32_e32 v119, v119
	v_exp_f32_e32 v122, v122
	v_exp_f32_e32 v123, v123
	v_pk_add_f32 v[120:121], v[118:119], v[120:121]
	v_cvt_pk_bf16_f32 v118, v118, v119
	v_pk_add_f32 v[160:161], v[122:123], v[120:121]
	v_cvt_pk_bf16_f32 v119, v122, v123
	s_waitcnt lgkmcnt(0)
	v_mfma_f32_32x32x16_bf16 v[64:79], v[238:241], v[128:131], v[64:79]
	s_mulk_i32 s24, 0x4800
	v_add_u32_e32 v159, s24, v218
	ds_read_b128 v[120:123], v159 offset:36864
	ds_read_b128 v[124:127], v159 offset:41472
	ds_read_b128 v[192:195], v159 offset:46080
	ds_read_b128 v[196:199], v159 offset:50688
	s_addk_i32 s25, 0x4800
	s_cmp_lg_u32 s30, 2
	s_cselect_b32 s24, s25, 0
	s_add_i32 s24, s24, 0
	v_add_u32_e32 v221, s24, v180
	v_add_u32_e32 v242, s24, v178
	ds_read_b128 v[226:229], v159 offset:36896
	ds_read_b128 v[230:233], v159 offset:41504
	ds_read_b128 v[234:237], v159 offset:46112
	ds_read_b128 v[238:241], v159 offset:50720
	s_waitcnt lgkmcnt(7)
	v_mfma_f32_32x32x16_bf16 v[16:31], v[120:123], v[112:115], v[16:31]
	v_fma_f32 v96, v96, s78, -v190
	v_fma_f32 v97, v97, s78, -v191
	v_fma_f32 v98, v98, s78, -v190
	v_fma_f32 v99, v99, s78, -v191
	v_exp_f32_e32 v96, v96
	v_exp_f32_e32 v97, v97
	v_exp_f32_e32 v98, v98
	v_exp_f32_e32 v99, v99
	v_pk_add_f32 v[120:121], v[96:97], v[160:161]
	v_cvt_pk_bf16_f32 v96, v96, v97
	v_pk_add_f32 v[120:121], v[98:99], v[120:121]
	v_cvt_pk_bf16_f32 v97, v98, v99
	s_waitcnt lgkmcnt(5)
	v_mfma_f32_32x32x16_bf16 v[48:63], v[124:127], v[112:115], v[48:63]
	v_mfma_f32_32x32x16_bf16 v[32:47], v[192:195], v[112:115], v[32:47]
	v_fma_f32 v98, v100, s78, -v190
	v_fma_f32 v99, v101, s78, -v191
	v_fma_f32 v100, v102, s78, -v190
	v_fma_f32 v101, v103, s78, -v191
	v_exp_f32_e32 v98, v98
	v_exp_f32_e32 v99, v99
	v_exp_f32_e32 v100, v100
	v_exp_f32_e32 v101, v101
	v_pk_add_f32 v[102:103], v[98:99], v[120:121]
	v_cvt_pk_bf16_f32 v98, v98, v99
	v_pk_add_f32 v[160:161], v[100:101], v[102:103]
	v_cvt_pk_bf16_f32 v99, v100, v101
	s_waitcnt lgkmcnt(4)
	v_mfma_f32_32x32x16_bf16 v[0:15], v[196:199], v[112:115], v[0:15]
	s_waitcnt vmcnt(3)
	ds_write_b128 v217, v[222:225] offset:18432
	ds_read_b128 v[100:103], v159 offset:36928
	ds_read_b128 v[112:115], v159 offset:41536
	ds_read_b128 v[120:123], v159 offset:46144
	ds_read_b128 v[124:127], v159 offset:50752
	s_waitcnt lgkmcnt(8)
	v_mfma_f32_32x32x16_bf16 v[16:31], v[226:229], v[116:119], v[16:31]
	v_fma_f32 v104, v104, s78, -v190
	v_fma_f32 v105, v105, s78, -v191
	v_fma_f32 v106, v106, s78, -v190
	v_fma_f32 v107, v107, s78, -v191
	v_exp_f32_e32 v104, v104
	v_exp_f32_e32 v105, v105
	v_exp_f32_e32 v106, v106
	v_exp_f32_e32 v107, v107
	v_pk_add_f32 v[160:161], v[104:105], v[160:161]
	v_cvt_pk_bf16_f32 v104, v104, v105
	v_pk_add_f32 v[160:161], v[106:107], v[160:161]
	v_cvt_pk_bf16_f32 v105, v106, v107
	s_waitcnt lgkmcnt(6)
	v_mfma_f32_32x32x16_bf16 v[48:63], v[230:233], v[116:119], v[48:63]
	v_mfma_f32_32x32x16_bf16 v[32:47], v[234:237], v[116:119], v[32:47]
	v_fma_f32 v106, v108, s78, -v190
	v_fma_f32 v107, v109, s78, -v191
	v_fma_f32 v108, v110, s78, -v190
	v_fma_f32 v109, v111, s78, -v191
	v_exp_f32_e32 v106, v106
	v_exp_f32_e32 v107, v107
	v_exp_f32_e32 v108, v108
	v_exp_f32_e32 v109, v109
	v_pk_add_f32 v[110:111], v[106:107], v[160:161]
	v_cvt_pk_bf16_f32 v106, v106, v107
	v_pk_add_f32 v[160:161], v[108:109], v[110:111]
	v_cvt_pk_bf16_f32 v107, v108, v109
	s_waitcnt lgkmcnt(5)
	v_mfma_f32_32x32x16_bf16 v[0:15], v[238:241], v[116:119], v[0:15]
	s_waitcnt vmcnt(2)
	ds_write_b128 v216, v[154:157] offset:18432
	ds_read_b128 v[108:111], v159 offset:36960
	ds_read_b128 v[116:119], v159 offset:41568
	ds_read_b128 v[154:157], v159 offset:46176
	ds_read_b128 v[190:193], v159 offset:50784
	s_waitcnt lgkmcnt(8)
	v_mfma_f32_32x32x16_bf16 v[16:31], v[100:103], v[96:99], v[16:31]
	s_mov_b32 s24, 0xf149f2ca
	v_max3_f32 v100, v80, s24, v81
	v_max3_f32 v100, v100, v82, v83
	v_max3_f32 v100, v100, v84, v85
	v_max3_f32 v100, v100, v86, v87
	s_waitcnt lgkmcnt(6)
	v_mfma_f32_32x32x16_bf16 v[48:63], v[112:115], v[96:99], v[48:63]
	v_mfma_f32_32x32x16_bf16 v[32:47], v[120:123], v[96:99], v[32:47]
	v_max3_f32 v100, v100, v88, v89
	v_max3_f32 v100, v100, v90, v91
	v_max3_f32 v100, v100, v92, v93
	v_max3_f32 v100, v100, v94, v95
	s_waitcnt lgkmcnt(5)
	v_mfma_f32_32x32x16_bf16 v[0:15], v[124:127], v[96:99], v[0:15]
	s_waitcnt vmcnt(1)
	ds_write_b128 v242, v[150:153] offset:36864
	s_waitcnt lgkmcnt(4)
	v_mfma_f32_32x32x16_bf16 v[16:31], v[108:111], v[104:107], v[16:31]
	v_max3_f32 v96, v100, v64, v65
	v_max3_f32 v96, v96, v66, v67
	v_max3_f32 v96, v96, v68, v69
	v_max3_f32 v96, v96, v70, v71
	s_waitcnt lgkmcnt(2)
	v_mfma_f32_32x32x16_bf16 v[48:63], v[116:119], v[104:107], v[48:63]
	v_mfma_f32_32x32x16_bf16 v[32:47], v[154:157], v[104:107], v[32:47]
	v_max3_f32 v96, v96, v72, v73
	v_max3_f32 v96, v96, v74, v75
	v_max3_f32 v96, v96, v76, v77
	v_max3_f32 v96, v96, v78, v79
	s_waitcnt lgkmcnt(1)
	v_mfma_f32_32x32x16_bf16 v[0:15], v[190:193], v[104:107], v[0:15]
	s_waitcnt vmcnt(0)
	ds_write_b128 v221, v[146:149] offset:36864
	v_add_f32_e32 v97, v160, v161
	v_add_f32_e32 v191, v158, v97
	v_mov_b32_e32 v97, v96
	s_nop 1
	v_permlane32_swap_b32_e32 v96, v97
	v_max_f32_e32 v96, v96, v97
	v_sub_f32_e32 v97, v96, v220
	v_mul_f32_e32 v97, 0x3e38aa3b, v97
	v_cmp_lt_f32_e32 vcc, s5, v97
	s_movk_i32 s27, 0x2000
	s_cbranch_vccz .LBB0_257
	v_max_f32_e32 v96, v96, v96
	v_max_f32_e32 v97, v220, v220
	v_max_f32_e32 v97, v97, v96
	v_sub_f32_e32 v96, v220, v97
	v_mul_f32_e32 v96, 0x3e38aa3b, v96
	v_exp_f32_e32 v96, v96
	v_mov_b32_e32 v220, v97
	v_pk_mul_f32 v[30:31], v[30:31], v[96:97] op_sel_hi:[1,0]
	v_pk_mul_f32 v[28:29], v[28:29], v[96:97] op_sel_hi:[1,0]
	v_pk_mul_f32 v[26:27], v[26:27], v[96:97] op_sel_hi:[1,0]
	v_pk_mul_f32 v[24:25], v[24:25], v[96:97] op_sel_hi:[1,0]
	v_pk_mul_f32 v[22:23], v[22:23], v[96:97] op_sel_hi:[1,0]
	v_pk_mul_f32 v[20:21], v[20:21], v[96:97] op_sel_hi:[1,0]
	v_pk_mul_f32 v[18:19], v[18:19], v[96:97] op_sel_hi:[1,0]
	v_pk_mul_f32 v[16:17], v[16:17], v[96:97] op_sel_hi:[1,0]
	v_pk_mul_f32 v[62:63], v[62:63], v[96:97] op_sel_hi:[1,0]
	v_pk_mul_f32 v[60:61], v[60:61], v[96:97] op_sel_hi:[1,0]
	v_pk_mul_f32 v[58:59], v[58:59], v[96:97] op_sel_hi:[1,0]
	v_pk_mul_f32 v[56:57], v[56:57], v[96:97] op_sel_hi:[1,0]
	v_pk_mul_f32 v[54:55], v[54:55], v[96:97] op_sel_hi:[1,0]
	v_pk_mul_f32 v[52:53], v[52:53], v[96:97] op_sel_hi:[1,0]
	v_pk_mul_f32 v[50:51], v[50:51], v[96:97] op_sel_hi:[1,0]
	v_pk_mul_f32 v[48:49], v[48:49], v[96:97] op_sel_hi:[1,0]
	v_pk_mul_f32 v[46:47], v[46:47], v[96:97] op_sel_hi:[1,0]
	v_pk_mul_f32 v[44:45], v[44:45], v[96:97] op_sel_hi:[1,0]
	v_pk_mul_f32 v[42:43], v[42:43], v[96:97] op_sel_hi:[1,0]
	v_pk_mul_f32 v[40:41], v[40:41], v[96:97] op_sel_hi:[1,0]
	v_pk_mul_f32 v[38:39], v[38:39], v[96:97] op_sel_hi:[1,0]
	v_pk_mul_f32 v[36:37], v[36:37], v[96:97] op_sel_hi:[1,0]
	v_pk_mul_f32 v[34:35], v[34:35], v[96:97] op_sel_hi:[1,0]
	v_pk_mul_f32 v[32:33], v[32:33], v[96:97] op_sel_hi:[1,0]
	v_pk_mul_f32 v[14:15], v[14:15], v[96:97] op_sel_hi:[1,0]
	v_pk_mul_f32 v[12:13], v[12:13], v[96:97] op_sel_hi:[1,0]
	v_pk_mul_f32 v[10:11], v[10:11], v[96:97] op_sel_hi:[1,0]
	v_pk_mul_f32 v[8:9], v[8:9], v[96:97] op_sel_hi:[1,0]
	v_pk_mul_f32 v[6:7], v[6:7], v[96:97] op_sel_hi:[1,0]
	v_pk_mul_f32 v[4:5], v[4:5], v[96:97] op_sel_hi:[1,0]
	v_pk_mul_f32 v[2:3], v[2:3], v[96:97] op_sel_hi:[1,0]
	v_pk_mul_f32 v[0:1], v[0:1], v[96:97] op_sel_hi:[1,0]
	v_mul_f32_e32 v191, v191, v96
	s_branch .LBB0_257
